# P15 epilogue de-serialised: 4 of the 8 second-half residual loads hoisted ahead of the first half's stores (on top of c18 GEMM loop changes)
# baseline (speedup 1.0000x reference)
; __device__ __forceinline__ unsigned cvt_pk_bf16(float lo, float hi) { unsigned r; asm volatile("v_cvt_pk_bf16_f32 %0, %1, %2" : "=v"(r) : "v"(lo), "v"(hi)); return r; }
; __device__ __forceinline__ float xsum16(float s) { auto r = __builtin_amdgcn_permlane16_swap(__float_as_uint(s), __float_as_uint(s), false, false); return __uint_as_float(r[0]) + __uint_as_float(r[1]); }
;     __device__ __forceinline__ void operator()(const f32x4 (&acc)[2][2][4][2], const Unit& u, int wr, int wc, int fr, int fq) const {
;         const int row0 = u.pm * BM + wr * 64 + fr, col0 = u.pn * BM + wc * 32 + 8 * fq;
; #pragma unroll
;         for (int ai = 0; ai < 2; ++ai) {
;             f32x4 b0[4][2], b1[4][2];
; #pragma unroll
;             for (int m = 0; m < 4; ++m)
; #pragma unroll
;                 for (int bj = 0; bj < 2; ++bj) { const size_t off = (size_t)(row0 + ai * HALF + m * 16) * ldc + col0 + bj * HALF;
;                     if (MODE == 0) { b0[m][bj] = *(const f32x4*)(xf + off); b1[m][bj] = *(const f32x4*)(xf + off + 4); }
;                     else { const u32x4 hv = *(const u32x4*)(H + off); b0[m][bj] = (f32x4){bf_lo(hv.x), bf_hi(hv.x), bf_lo(hv.y), bf_hi(hv.y)}; b1[m][bj] = (f32x4){bf_lo(hv.z), bf_hi(hv.z), bf_lo(hv.w), bf_hi(hv.w)}; } }
;             asm volatile("" ::: "memory");
; #pragma unroll
;             for (int m = 0; m < 4; ++m) { const int row = row0 + ai * HALF + m * 16; float s = 0.f;
; #pragma unroll
;                 for (int bj = 0; bj < 2; ++bj) { const size_t off = (size_t)row * ldc + col0 + bj * HALF;
;                     const f32x4 al4 = {alpha, alpha, alpha, alpha}; const f32x4 h0 = __builtin_elementwise_fma(acc[ai][bj][m][0], al4, b0[m][bj]), h1 = __builtin_elementwise_fma(acc[ai][bj][m][1], al4, b1[m][bj]);
;                     if (MODE == 2) { *(f32x4*)(outf + off) = h0; *(f32x4*)(outf + off + 4) = h1; }
;                     else { u32x4 w; w.x = cvt_pk_bf16(h0.x, h0.y); w.y = cvt_pk_bf16(h0.z, h0.w); w.z = cvt_pk_bf16(h1.x, h1.y); w.w = cvt_pk_bf16(h1.z, h1.w); *(u32x4*)(H + off) = w;
;                         s = sq2bf(w.x, sq2bf(w.y, sq2bf(w.z, sq2bf(w.w, s)))); } }
;                 if (MODE != 2) { s = xsum32(xsum16(s)); if (fq == 0) atomicAdd(rowss + row, s); } }
.LBB0_1428:
	v_mov_b32_e32 v0, v254
	s_lshl_b32 s19, s48, 8
	v_readfirstlane_b32 s18, v0
	s_ashr_i32 s20, s18, 2
	s_andn2_b32 s20, s20, 63
	s_lshr_b32 s18, s18, 1
	s_add_i32 s20, s20, s19
	s_lshl_b32 s19, s43, 8
	s_and_b32 s18, s18, 0x60
	v_and_or_b32 v146, v0, 15, s20
	s_or_b32 s18, s18, s19
	v_lshrrev_b32_e32 v0, 1, v0
	v_and_or_b32 v142, v0, 24, s18
	v_ashrrev_i32_e32 v143, 31, v142
	v_ashrrev_i32_e32 v147, 31, v146
	v_lshl_add_u64 v[148:149], v[142:143], 1, s[36:37]
	v_lshlrev_b64 v[150:151], 13, v[146:147]
	v_lshl_add_u64 v[150:151], v[148:149], 0, v[150:151]
	global_load_dwordx4 v[156:159], v[150:151], off
	global_load_dwordx4 v[160:163], v[150:151], off offset:256
	v_or_b32_e32 v188, 16, v146
	v_ashrrev_i32_e32 v189, 31, v188
	v_lshlrev_b64 v[150:151], 13, v[188:189]
	v_or_b32_e32 v190, 32, v146
	v_lshl_add_u64 v[150:151], v[148:149], 0, v[150:151]
	v_ashrrev_i32_e32 v191, 31, v190
	global_load_dwordx4 v[164:167], v[150:151], off
	global_load_dwordx4 v[168:171], v[150:151], off offset:256
	v_lshlrev_b64 v[150:151], 13, v[190:191]
	v_lshl_add_u64 v[150:151], v[148:149], 0, v[150:151]
	global_load_dwordx4 v[172:175], v[150:151], off
	global_load_dwordx4 v[176:179], v[150:151], off offset:256
	v_or_b32_e32 v150, 48, v146
	v_ashrrev_i32_e32 v151, 31, v150
	v_lshlrev_b64 v[180:181], 13, v[150:151]
	v_lshl_add_u64 v[184:185], v[148:149], 0, v[180:181]
	global_load_dwordx4 v[180:183], v[184:185], off
	s_nop 0
	global_load_dwordx4 v[184:187], v[184:185], off offset:256
	v_add_u32_e32 v240, 0x80, v146
	v_ashrrev_i32_e32 v241, 31, v240
	v_lshlrev_b64 v[240:241], 13, v[240:241]
	v_lshl_add_u64 v[240:241], v[148:149], 0, v[240:241]
	global_load_dwordx4 v[224:227], v[240:241], off
	global_load_dwordx4 v[228:231], v[240:241], off offset:256
	v_add_u32_e32 v240, 0x90, v146
	v_ashrrev_i32_e32 v241, 31, v240
	v_lshlrev_b64 v[240:241], 13, v[240:241]
	v_lshl_add_u64 v[240:241], v[148:149], 0, v[240:241]
	global_load_dwordx4 v[232:235], v[240:241], off
	global_load_dwordx4 v[236:239], v[240:241], off offset:256
	s_and_b64 vcc, exec, s[0:1]
	s_mov_b64 s[0:1], -1
	s_waitcnt vmcnt(4)
	v_lshlrev_b32_e32 v192, 16, v156
	v_and_b32_e32 v193, 0xffff0000, v156
	v_lshlrev_b32_e32 v156, 16, v157
	v_and_b32_e32 v157, 0xffff0000, v157
	v_lshlrev_b32_e32 v194, 16, v158
	v_and_b32_e32 v195, 0xffff0000, v158
	v_lshlrev_b32_e32 v158, 16, v159
	v_and_b32_e32 v159, 0xffff0000, v159
	v_pk_fma_f32 v[128:129], v[128:129], 0.5, v[156:157] op_sel_hi:[1,0,1]
	v_pk_fma_f32 v[156:157], v[122:123], 0.5, v[194:195] op_sel_hi:[1,0,1]
	v_lshlrev_b64 v[122:123], 14, v[146:147]
	v_lshlrev_b32_e32 v196, 16, v160
	v_and_b32_e32 v197, 0xffff0000, v160
	v_lshlrev_b32_e32 v160, 16, v161
	v_and_b32_e32 v161, 0xffff0000, v161
	v_lshlrev_b32_e32 v198, 16, v162
	v_and_b32_e32 v199, 0xffff0000, v162
	v_pk_fma_f32 v[158:159], v[124:125], 0.5, v[158:159] op_sel_hi:[1,0,1]
	v_lshl_add_u64 v[124:125], s[62:63], 0, v[122:123]
	v_lshlrev_b64 v[122:123], 2, v[142:143]
	v_lshlrev_b32_e32 v162, 16, v163
	v_and_b32_e32 v163, 0xffff0000, v163
	v_pk_fma_f32 v[126:127], v[126:127], 0.5, v[192:193] op_sel_hi:[1,0,1]
	v_lshl_add_u64 v[124:125], v[124:125], 0, v[122:123]
	v_pk_fma_f32 v[120:121], v[120:121], 0.5, v[160:161] op_sel_hi:[1,0,1]
	v_pk_fma_f32 v[118:119], v[118:119], 0.5, v[196:197] op_sel_hi:[1,0,1]
	v_pk_fma_f32 v[114:115], v[114:115], 0.5, v[198:199] op_sel_hi:[1,0,1]
	global_store_dwordx4 v[124:125], v[126:129], off
	global_store_dwordx4 v[124:125], v[156:159], off offset:16
	v_pk_fma_f32 v[116:117], v[116:117], 0.5, v[162:163] op_sel_hi:[1,0,1]
	global_store_dwordx4 v[124:125], v[118:121], off offset:512
	global_store_dwordx4 v[124:125], v[114:117], off offset:528
	v_lshlrev_b32_e32 v200, 16, v164
	v_and_b32_e32 v201, 0xffff0000, v164
	v_lshlrev_b64 v[114:115], 14, v[188:189]
	v_lshlrev_b32_e32 v164, 16, v165
	v_and_b32_e32 v165, 0xffff0000, v165
	v_lshlrev_b32_e32 v204, 16, v168
	v_and_b32_e32 v205, 0xffff0000, v168
	v_lshlrev_b32_e32 v168, 16, v169
	v_and_b32_e32 v169, 0xffff0000, v169
	v_lshlrev_b32_e32 v206, 16, v170
	v_and_b32_e32 v207, 0xffff0000, v170
	v_lshl_add_u64 v[114:115], s[62:63], 0, v[114:115]
	v_lshlrev_b32_e32 v202, 16, v166
	v_and_b32_e32 v203, 0xffff0000, v166
	v_lshlrev_b32_e32 v166, 16, v167
	v_and_b32_e32 v167, 0xffff0000, v167
	v_lshlrev_b32_e32 v170, 16, v171
	v_and_b32_e32 v171, 0xffff0000, v171
	v_pk_fma_f32 v[112:113], v[112:113], 0.5, v[164:165] op_sel_hi:[1,0,1]
	v_pk_fma_f32 v[110:111], v[110:111], 0.5, v[200:201] op_sel_hi:[1,0,1]
	v_lshl_add_u64 v[114:115], v[114:115], 0, v[122:123]
	v_pk_fma_f32 v[104:105], v[104:105], 0.5, v[168:169] op_sel_hi:[1,0,1]
	v_pk_fma_f32 v[102:103], v[102:103], 0.5, v[204:205] op_sel_hi:[1,0,1]
	v_pk_fma_f32 v[98:99], v[98:99], 0.5, v[206:207] op_sel_hi:[1,0,1]
	v_pk_fma_f32 v[108:109], v[108:109], 0.5, v[166:167] op_sel_hi:[1,0,1]
	v_pk_fma_f32 v[106:107], v[106:107], 0.5, v[202:203] op_sel_hi:[1,0,1]
	global_store_dwordx4 v[114:115], v[110:113], off
	global_store_dwordx4 v[114:115], v[106:109], off offset:16
	v_pk_fma_f32 v[100:101], v[100:101], 0.5, v[170:171] op_sel_hi:[1,0,1]
	global_store_dwordx4 v[114:115], v[102:105], off offset:512
	global_store_dwordx4 v[114:115], v[98:101], off offset:528
	v_lshlrev_b32_e32 v208, 16, v172
	v_and_b32_e32 v209, 0xffff0000, v172
	v_lshlrev_b64 v[98:99], 14, v[190:191]
	v_lshlrev_b32_e32 v172, 16, v173
	v_and_b32_e32 v173, 0xffff0000, v173
	v_lshlrev_b32_e32 v212, 16, v176
	v_and_b32_e32 v213, 0xffff0000, v176
	v_lshlrev_b32_e32 v176, 16, v177
	v_and_b32_e32 v177, 0xffff0000, v177
	v_lshlrev_b32_e32 v214, 16, v178
	v_and_b32_e32 v215, 0xffff0000, v178
	v_lshl_add_u64 v[98:99], s[62:63], 0, v[98:99]
; __device__ __forceinline__ unsigned cvt_pk_bf16(float lo, float hi) { unsigned r; asm volatile("v_cvt_pk_bf16_f32 %0, %1, %2" : "=v"(r) : "v"(lo), "v"(hi)); return r; }
; __device__ __forceinline__ float xsum16(float s) { auto r = __builtin_amdgcn_permlane16_swap(__float_as_uint(s), __float_as_uint(s), false, false); return __uint_as_float(r[0]) + __uint_as_float(r[1]); }
; __device__ __forceinline__ float xsum32(float s) { auto r = __builtin_amdgcn_permlane32_swap(__float_as_uint(s), __float_as_uint(s), false, false); return __uint_as_float(r[0]) + __uint_as_float(r[1]); }
;     __device__ __forceinline__ void operator()(const f32x4 (&acc)[2][2][4][2], const Unit& u, int wr, int wc, int fr, int fq) const {
;     ...
;         for (int ai = 0; ai < 2; ++ai) {
;             f32x4 b0[4][2], b1[4][2];
; #pragma unroll
;             for (int m = 0; m < 4; ++m)
; #pragma unroll
;                 for (int bj = 0; bj < 2; ++bj) { const size_t off = (size_t)(row0 + ai * HALF + m * 16) * ldc + col0 + bj * HALF;
;                     if (MODE == 0) { b0[m][bj] = *(const f32x4*)(xf + off); b1[m][bj] = *(const f32x4*)(xf + off + 4); }
;                     else { const u32x4 hv = *(const u32x4*)(H + off); b0[m][bj] = (f32x4){bf_lo(hv.x), bf_hi(hv.x), bf_lo(hv.y), bf_hi(hv.y)}; b1[m][bj] = (f32x4){bf_lo(hv.z), bf_hi(hv.z), bf_lo(hv.w), bf_hi(hv.w)}; } }
;             asm volatile("" ::: "memory");
; #pragma unroll
;             for (int m = 0; m < 4; ++m) { const int row = row0 + ai * HALF + m * 16; float s = 0.f;
; #pragma unroll
;                 for (int bj = 0; bj < 2; ++bj) { const size_t off = (size_t)row * ldc + col0 + bj * HALF;
;                     const f32x4 al4 = {alpha, alpha, alpha, alpha}; const f32x4 h0 = __builtin_elementwise_fma(acc[ai][bj][m][0], al4, b0[m][bj]), h1 = __builtin_elementwise_fma(acc[ai][bj][m][1], al4, b1[m][bj]);
;                     if (MODE == 2) { *(f32x4*)(outf + off) = h0; *(f32x4*)(outf + off + 4) = h1; }
;                     else { u32x4 w; w.x = cvt_pk_bf16(h0.x, h0.y); w.y = cvt_pk_bf16(h0.z, h0.w); w.z = cvt_pk_bf16(h1.x, h1.y); w.w = cvt_pk_bf16(h1.z, h1.w); *(u32x4*)(H + off) = w;
;                         s = sq2bf(w.x, sq2bf(w.y, sq2bf(w.z, sq2bf(w.w, s)))); } }
;                 if (MODE != 2) { s = xsum32(xsum16(s)); if (fq == 0) atomicAdd(rowss + row, s); } }
	v_lshlrev_b32_e32 v210, 16, v174
	v_and_b32_e32 v211, 0xffff0000, v174
	v_lshlrev_b32_e32 v174, 16, v175
	v_and_b32_e32 v175, 0xffff0000, v175
	v_lshlrev_b32_e32 v178, 16, v179
	v_and_b32_e32 v179, 0xffff0000, v179
	v_pk_fma_f32 v[96:97], v[96:97], 0.5, v[172:173] op_sel_hi:[1,0,1]
	v_pk_fma_f32 v[94:95], v[94:95], 0.5, v[208:209] op_sel_hi:[1,0,1]
	v_lshl_add_u64 v[98:99], v[98:99], 0, v[122:123]
	v_pk_fma_f32 v[88:89], v[88:89], 0.5, v[176:177] op_sel_hi:[1,0,1]
	v_pk_fma_f32 v[86:87], v[86:87], 0.5, v[212:213] op_sel_hi:[1,0,1]
	v_pk_fma_f32 v[82:83], v[82:83], 0.5, v[214:215] op_sel_hi:[1,0,1]
	v_pk_fma_f32 v[92:93], v[92:93], 0.5, v[174:175] op_sel_hi:[1,0,1]
	v_pk_fma_f32 v[90:91], v[90:91], 0.5, v[210:211] op_sel_hi:[1,0,1]
	global_store_dwordx4 v[98:99], v[94:97], off
	global_store_dwordx4 v[98:99], v[90:93], off offset:16
	v_pk_fma_f32 v[84:85], v[84:85], 0.5, v[178:179] op_sel_hi:[1,0,1]
	global_store_dwordx4 v[98:99], v[86:89], off offset:512
	global_store_dwordx4 v[98:99], v[82:85], off offset:528
	v_lshlrev_b32_e32 v216, 16, v180
	v_and_b32_e32 v217, 0xffff0000, v180
	v_lshlrev_b64 v[82:83], 14, v[150:151]
	v_lshlrev_b32_e32 v180, 16, v181
	v_and_b32_e32 v181, 0xffff0000, v181
	v_lshlrev_b32_e32 v220, 16, v184
	v_and_b32_e32 v221, 0xffff0000, v184
	v_lshlrev_b32_e32 v184, 16, v185
	v_and_b32_e32 v185, 0xffff0000, v185
	v_lshlrev_b32_e32 v222, 16, v186
	v_and_b32_e32 v223, 0xffff0000, v186
	v_lshl_add_u64 v[82:83], s[62:63], 0, v[82:83]
	v_add_u32_e32 v100, 0x80, v146
	v_lshlrev_b32_e32 v218, 16, v182
	v_and_b32_e32 v219, 0xffff0000, v182
	v_lshlrev_b32_e32 v182, 16, v183
	v_and_b32_e32 v183, 0xffff0000, v183
	v_lshlrev_b32_e32 v186, 16, v187
	v_and_b32_e32 v187, 0xffff0000, v187
	v_pk_fma_f32 v[80:81], v[80:81], 0.5, v[180:181] op_sel_hi:[1,0,1]
	v_pk_fma_f32 v[78:79], v[78:79], 0.5, v[216:217] op_sel_hi:[1,0,1]
	v_lshl_add_u64 v[82:83], v[82:83], 0, v[122:123]
	v_pk_fma_f32 v[72:73], v[72:73], 0.5, v[184:185] op_sel_hi:[1,0,1]
	v_pk_fma_f32 v[70:71], v[70:71], 0.5, v[220:221] op_sel_hi:[1,0,1]
	v_pk_fma_f32 v[66:67], v[66:67], 0.5, v[222:223] op_sel_hi:[1,0,1]
	v_ashrrev_i32_e32 v101, 31, v100
	v_pk_fma_f32 v[76:77], v[76:77], 0.5, v[182:183] op_sel_hi:[1,0,1]
	v_pk_fma_f32 v[74:75], v[74:75], 0.5, v[218:219] op_sel_hi:[1,0,1]
	global_store_dwordx4 v[82:83], v[78:81], off
	global_store_dwordx4 v[82:83], v[74:77], off offset:16
	v_pk_fma_f32 v[68:69], v[68:69], 0.5, v[186:187] op_sel_hi:[1,0,1]
	global_store_dwordx4 v[82:83], v[70:73], off offset:512
	global_store_dwordx4 v[82:83], v[66:69], off offset:528
	v_add_u32_e32 v102, 0x90, v146
	v_ashrrev_i32_e32 v103, 31, v102
	v_lshlrev_b64 v[66:67], 13, v[100:101]
	v_lshl_add_u64 v[66:67], v[148:149], 0, v[66:67]
	s_waitcnt vmcnt(16)
	v_mov_b64_e32 v[68:69], v[224:225]
	v_mov_b64_e32 v[70:71], v[226:227]
	v_mov_b64_e32 v[72:73], v[228:229]
	v_mov_b64_e32 v[74:75], v[230:231]
	v_lshlrev_b64 v[66:67], 13, v[102:103]
	v_add_u32_e32 v104, 0xa0, v146
	v_lshl_add_u64 v[66:67], v[148:149], 0, v[66:67]
	v_ashrrev_i32_e32 v105, 31, v104
	v_mov_b64_e32 v[76:77], v[232:233]
	v_mov_b64_e32 v[78:79], v[234:235]
	v_mov_b64_e32 v[80:81], v[236:237]
	v_mov_b64_e32 v[82:83], v[238:239]
	v_lshlrev_b64 v[66:67], 13, v[104:105]
	v_lshl_add_u64 v[66:67], v[148:149], 0, v[66:67]
	global_load_dwordx4 v[84:87], v[66:67], off
	global_load_dwordx4 v[88:91], v[66:67], off offset:256
	v_add_u32_e32 v66, 0xb0, v146
	v_ashrrev_i32_e32 v67, 31, v66
	v_lshlrev_b64 v[92:93], 13, v[66:67]
	v_lshl_add_u64 v[96:97], v[148:149], 0, v[92:93]
	global_load_dwordx4 v[92:95], v[96:97], off
	s_nop 0
	global_load_dwordx4 v[96:99], v[96:97], off offset:256
	v_lshlrev_b32_e32 v106, 16, v68
	v_and_b32_e32 v107, 0xffff0000, v68
	v_lshlrev_b32_e32 v68, 16, v69
	v_and_b32_e32 v69, 0xffff0000, v69
	v_pk_fma_f32 v[64:65], v[64:65], 0.5, v[68:69] op_sel_hi:[1,0,1]
	v_lshlrev_b64 v[68:69], 14, v[100:101]
	v_lshlrev_b32_e32 v110, 16, v72
	v_and_b32_e32 v111, 0xffff0000, v72
	v_lshlrev_b32_e32 v72, 16, v73
	v_and_b32_e32 v73, 0xffff0000, v73
	v_lshlrev_b32_e32 v112, 16, v74
	v_and_b32_e32 v113, 0xffff0000, v74
	v_lshl_add_u64 v[68:69], s[62:63], 0, v[68:69]
	v_lshlrev_b32_e32 v108, 16, v70
	v_and_b32_e32 v109, 0xffff0000, v70
	v_lshlrev_b32_e32 v70, 16, v71
	v_and_b32_e32 v71, 0xffff0000, v71
	v_lshlrev_b32_e32 v74, 16, v75
	v_and_b32_e32 v75, 0xffff0000, v75
	v_pk_fma_f32 v[62:63], v[62:63], 0.5, v[106:107] op_sel_hi:[1,0,1]
	v_lshl_add_u64 v[68:69], v[68:69], 0, v[122:123]
	v_pk_fma_f32 v[56:57], v[56:57], 0.5, v[72:73] op_sel_hi:[1,0,1]
	v_pk_fma_f32 v[54:55], v[54:55], 0.5, v[110:111] op_sel_hi:[1,0,1]
	v_pk_fma_f32 v[50:51], v[50:51], 0.5, v[112:113] op_sel_hi:[1,0,1]
	v_pk_fma_f32 v[60:61], v[60:61], 0.5, v[70:71] op_sel_hi:[1,0,1]
	v_pk_fma_f32 v[58:59], v[58:59], 0.5, v[108:109] op_sel_hi:[1,0,1]
	global_store_dwordx4 v[68:69], v[62:65], off
	global_store_dwordx4 v[68:69], v[58:61], off offset:16
	v_pk_fma_f32 v[52:53], v[52:53], 0.5, v[74:75] op_sel_hi:[1,0,1]
	global_store_dwordx4 v[68:69], v[54:57], off offset:512
	global_store_dwordx4 v[68:69], v[50:53], off offset:528
	v_lshlrev_b32_e32 v114, 16, v76
	v_and_b32_e32 v115, 0xffff0000, v76
	v_lshlrev_b64 v[50:51], 14, v[102:103]
	v_lshlrev_b32_e32 v76, 16, v77
	v_and_b32_e32 v77, 0xffff0000, v77
	v_lshlrev_b32_e32 v118, 16, v80
	v_and_b32_e32 v119, 0xffff0000, v80
	v_lshlrev_b32_e32 v80, 16, v81
	v_and_b32_e32 v81, 0xffff0000, v81
	v_lshlrev_b32_e32 v120, 16, v82
	v_and_b32_e32 v121, 0xffff0000, v82
	v_lshl_add_u64 v[50:51], s[62:63], 0, v[50:51]
	v_lshlrev_b32_e32 v116, 16, v78
	v_and_b32_e32 v117, 0xffff0000, v78
	v_lshlrev_b32_e32 v78, 16, v79
	v_and_b32_e32 v79, 0xffff0000, v79
	v_lshlrev_b32_e32 v82, 16, v83
	v_and_b32_e32 v83, 0xffff0000, v83
	v_pk_fma_f32 v[48:49], v[48:49], 0.5, v[76:77] op_sel_hi:[1,0,1]
	v_pk_fma_f32 v[46:47], v[46:47], 0.5, v[114:115] op_sel_hi:[1,0,1]
	v_lshl_add_u64 v[50:51], v[50:51], 0, v[122:123]
	v_pk_fma_f32 v[40:41], v[40:41], 0.5, v[80:81] op_sel_hi:[1,0,1]
	v_pk_fma_f32 v[38:39], v[38:39], 0.5, v[118:119] op_sel_hi:[1,0,1]
	v_pk_fma_f32 v[34:35], v[34:35], 0.5, v[120:121] op_sel_hi:[1,0,1]
	v_pk_fma_f32 v[44:45], v[44:45], 0.5, v[78:79] op_sel_hi:[1,0,1]
	v_pk_fma_f32 v[42:43], v[42:43], 0.5, v[116:117] op_sel_hi:[1,0,1]
	global_store_dwordx4 v[50:51], v[46:49], off
	global_store_dwordx4 v[50:51], v[42:45], off offset:16
	v_pk_fma_f32 v[36:37], v[36:37], 0.5, v[82:83] op_sel_hi:[1,0,1]
	global_store_dwordx4 v[50:51], v[38:41], off offset:512
	global_store_dwordx4 v[50:51], v[34:37], off offset:528
	s_waitcnt vmcnt(11)
; __device__ __forceinline__ unsigned cvt_pk_bf16(float lo, float hi) { unsigned r; asm volatile("v_cvt_pk_bf16_f32 %0, %1, %2" : "=v"(r) : "v"(lo), "v"(hi)); return r; }
; __device__ __forceinline__ float xsum16(float s) { auto r = __builtin_amdgcn_permlane16_swap(__float_as_uint(s), __float_as_uint(s), false, false); return __uint_as_float(r[0]) + __uint_as_float(r[1]); }
; __device__ __forceinline__ float xsum32(float s) { auto r = __builtin_amdgcn_permlane32_swap(__float_as_uint(s), __float_as_uint(s), false, false); return __uint_as_float(r[0]) + __uint_as_float(r[1]); }
; __device__ __forceinline__ float sq2bf(unsigned w, float c) { const s16x2_t a = __builtin_bit_cast(s16x2_t, w); return __builtin_amdgcn_fdot2_f32_bf16(a, a, c, false); }
;     __device__ __forceinline__ void operator()(const f32x4 (&acc)[2][2][4][2], const Unit& u, int wr, int wc, int fr, int fq) const {
;     ...
;             for (int m = 0; m < 4; ++m) { const int row = row0 + ai * HALF + m * 16; float s = 0.f;
; #pragma unroll
;                 for (int bj = 0; bj < 2; ++bj) { const size_t off = (size_t)row * ldc + col0 + bj * HALF;
;                     const f32x4 al4 = {alpha, alpha, alpha, alpha}; const f32x4 h0 = __builtin_elementwise_fma(acc[ai][bj][m][0], al4, b0[m][bj]), h1 = __builtin_elementwise_fma(acc[ai][bj][m][1], al4, b1[m][bj]);
;                     if (MODE == 2) { *(f32x4*)(outf + off) = h0; *(f32x4*)(outf + off + 4) = h1; }
;                     else { u32x4 w; w.x = cvt_pk_bf16(h0.x, h0.y); w.y = cvt_pk_bf16(h0.z, h0.w); w.z = cvt_pk_bf16(h1.x, h1.y); w.w = cvt_pk_bf16(h1.z, h1.w); *(u32x4*)(H + off) = w;
;                         s = sq2bf(w.x, sq2bf(w.y, sq2bf(w.z, sq2bf(w.w, s)))); } }
;                 if (MODE != 2) { s = xsum32(xsum16(s)); if (fq == 0) atomicAdd(rowss + row, s); } }
	v_lshlrev_b32_e32 v124, 16, v84
	v_and_b32_e32 v125, 0xffff0000, v84
	v_lshlrev_b64 v[34:35], 14, v[104:105]
	v_lshlrev_b32_e32 v84, 16, v85
	v_and_b32_e32 v85, 0xffff0000, v85
	s_waitcnt vmcnt(10)
	v_lshlrev_b32_e32 v128, 16, v88
	v_and_b32_e32 v129, 0xffff0000, v88
	v_lshlrev_b32_e32 v88, 16, v89
	v_and_b32_e32 v89, 0xffff0000, v89
	v_lshlrev_b32_e32 v142, 16, v90
	v_and_b32_e32 v143, 0xffff0000, v90
	v_lshl_add_u64 v[34:35], s[62:63], 0, v[34:35]
	v_lshlrev_b32_e32 v126, 16, v86
	v_and_b32_e32 v127, 0xffff0000, v86
	v_lshlrev_b32_e32 v86, 16, v87
	v_and_b32_e32 v87, 0xffff0000, v87
	v_lshlrev_b32_e32 v90, 16, v91
	v_and_b32_e32 v91, 0xffff0000, v91
	v_pk_fma_f32 v[32:33], v[32:33], 0.5, v[84:85] op_sel_hi:[1,0,1]
	v_pk_fma_f32 v[30:31], v[30:31], 0.5, v[124:125] op_sel_hi:[1,0,1]
	v_lshl_add_u64 v[34:35], v[34:35], 0, v[122:123]
	v_pk_fma_f32 v[24:25], v[24:25], 0.5, v[88:89] op_sel_hi:[1,0,1]
	v_pk_fma_f32 v[22:23], v[22:23], 0.5, v[128:129] op_sel_hi:[1,0,1]
	v_pk_fma_f32 v[18:19], v[18:19], 0.5, v[142:143] op_sel_hi:[1,0,1]
	v_pk_fma_f32 v[28:29], v[28:29], 0.5, v[86:87] op_sel_hi:[1,0,1]
	v_pk_fma_f32 v[26:27], v[26:27], 0.5, v[126:127] op_sel_hi:[1,0,1]
	global_store_dwordx4 v[34:35], v[30:33], off
	global_store_dwordx4 v[34:35], v[26:29], off offset:16
	v_pk_fma_f32 v[20:21], v[20:21], 0.5, v[90:91] op_sel_hi:[1,0,1]
	global_store_dwordx4 v[34:35], v[22:25], off offset:512
	global_store_dwordx4 v[34:35], v[18:21], off offset:528
	s_waitcnt vmcnt(13)
	v_lshlrev_b32_e32 v146, 16, v92
	v_and_b32_e32 v147, 0xffff0000, v92
	v_lshlrev_b64 v[18:19], 14, v[66:67]
	v_lshlrev_b32_e32 v92, 16, v93
	v_and_b32_e32 v93, 0xffff0000, v93
	s_waitcnt vmcnt(12)
	v_lshlrev_b32_e32 v150, 16, v96
	v_and_b32_e32 v151, 0xffff0000, v96
	v_lshlrev_b32_e32 v96, 16, v97
	v_and_b32_e32 v97, 0xffff0000, v97
	v_lshl_add_u64 v[18:19], s[62:63], 0, v[18:19]
	v_lshlrev_b32_e32 v148, 16, v94
	v_and_b32_e32 v149, 0xffff0000, v94
	v_lshlrev_b32_e32 v94, 16, v95
	v_and_b32_e32 v95, 0xffff0000, v95
	v_lshlrev_b32_e32 v156, 16, v98
	v_and_b32_e32 v157, 0xffff0000, v98
	v_lshlrev_b32_e32 v98, 16, v99
	v_and_b32_e32 v99, 0xffff0000, v99
	v_pk_fma_f32 v[16:17], v[16:17], 0.5, v[92:93] op_sel_hi:[1,0,1]
	v_pk_fma_f32 v[14:15], v[14:15], 0.5, v[146:147] op_sel_hi:[1,0,1]
	v_lshl_add_u64 v[18:19], v[18:19], 0, v[122:123]
	v_pk_fma_f32 v[8:9], v[8:9], 0.5, v[96:97] op_sel_hi:[1,0,1]
	v_pk_fma_f32 v[6:7], v[6:7], 0.5, v[150:151] op_sel_hi:[1,0,1]
	v_pk_fma_f32 v[12:13], v[12:13], 0.5, v[94:95] op_sel_hi:[1,0,1]
	v_pk_fma_f32 v[10:11], v[10:11], 0.5, v[148:149] op_sel_hi:[1,0,1]
	global_store_dwordx4 v[18:19], v[14:17], off
	global_store_dwordx4 v[18:19], v[10:13], off offset:16
	v_pk_fma_f32 v[4:5], v[4:5], 0.5, v[98:99] op_sel_hi:[1,0,1]
	v_pk_fma_f32 v[2:3], v[2:3], 0.5, v[156:157] op_sel_hi:[1,0,1]
	global_store_dwordx4 v[18:19], v[6:9], off offset:512
	global_store_dwordx4 v[18:19], v[2:5], off offset:528
	s_cbranch_vccnz .LBB0_1413
	s_andn2_b64 vcc, exec, s[6:7]
	s_cbranch_vccnz .LBB0_1412
	s_barrier
	s_branch .LBB0_1412
